# weight-convert tiles: the 16 row loads issued together with one wait (were load/wait/ds_write x16)
# speedup vs baseline: 1.5833x; 1.0126x over previous
.LBB0_65:
	v_mov_b32_e32 v152, 0
	v_mov_b32_e32 v153, 0
	v_mov_b32_e32 v154, 0
	v_mov_b32_e32 v155, 0
	v_mov_b32_e32 v156, 0
	v_mov_b32_e32 v157, 0
	v_mov_b32_e32 v158, 0
	v_mov_b32_e32 v159, 0
	v_mov_b32_e32 v160, 0
	v_mov_b32_e32 v161, 0
	v_mov_b32_e32 v162, 0
	v_mov_b32_e32 v163, 0
	v_mov_b32_e32 v164, 0
	v_mov_b32_e32 v165, 0
	v_mov_b32_e32 v166, 0
	v_mov_b32_e32 v167, 0
	s_and_saveexec_b64 s[16:17], vcc
	s_cbranch_execz .Lcva_skip
	v_lshl_add_u64 v[168:169], v[4:5], 0, v[12:13]
	global_load_dword v152, v[168:169], off
	v_lshl_add_u64 v[168:169], v[4:5], 0, v[10:11]
	global_load_dword v153, v[168:169], off
	v_lshl_add_u64 v[168:169], v[4:5], 0, v[8:9]
	global_load_dword v154, v[168:169], off
	v_lshl_add_u64 v[168:169], v[4:5], 0, v[6:7]
	global_load_dword v155, v[168:169], off
	v_lshl_add_u64 v[4:5], v[4:5], 0, s[14:15]
	v_lshl_add_u64 v[168:169], v[4:5], 0, v[12:13]
	global_load_dword v156, v[168:169], off
	v_lshl_add_u64 v[168:169], v[4:5], 0, v[10:11]
	global_load_dword v157, v[168:169], off
	v_lshl_add_u64 v[168:169], v[4:5], 0, v[8:9]
	global_load_dword v158, v[168:169], off
	v_lshl_add_u64 v[168:169], v[4:5], 0, v[6:7]
	global_load_dword v159, v[168:169], off
	v_lshl_add_u64 v[4:5], v[4:5], 0, s[14:15]
	v_lshl_add_u64 v[168:169], v[4:5], 0, v[12:13]
	global_load_dword v160, v[168:169], off
	v_lshl_add_u64 v[168:169], v[4:5], 0, v[10:11]
	global_load_dword v161, v[168:169], off
	v_lshl_add_u64 v[168:169], v[4:5], 0, v[8:9]
	global_load_dword v162, v[168:169], off
	v_lshl_add_u64 v[168:169], v[4:5], 0, v[6:7]
	global_load_dword v163, v[168:169], off
	v_lshl_add_u64 v[4:5], v[4:5], 0, s[14:15]
	v_lshl_add_u64 v[168:169], v[4:5], 0, v[12:13]
	global_load_dword v164, v[168:169], off
	v_lshl_add_u64 v[168:169], v[4:5], 0, v[10:11]
	global_load_dword v165, v[168:169], off
	v_lshl_add_u64 v[168:169], v[4:5], 0, v[8:9]
	global_load_dword v166, v[168:169], off
	v_lshl_add_u64 v[168:169], v[4:5], 0, v[6:7]
	global_load_dword v167, v[168:169], off
	v_lshl_add_u64 v[4:5], v[4:5], 0, s[14:15]
.Lcva_skip:
	s_or_b64 exec, exec, s[16:17]
	s_waitcnt vmcnt(0)
	v_add_u32_e32 v170, 0x0, v2
	ds_write_b32 v170, v152
	ds_write_b32 v170, v153 offset:1040
	ds_write_b32 v170, v154 offset:2080
	ds_write_b32 v170, v155 offset:3120
	v_add_u32_e32 v170, 0x1040, v2
	ds_write_b32 v170, v156
	ds_write_b32 v170, v157 offset:1040
	ds_write_b32 v170, v158 offset:2080
	ds_write_b32 v170, v159 offset:3120
	v_add_u32_e32 v170, 0x2080, v2
	ds_write_b32 v170, v160
	ds_write_b32 v170, v161 offset:1040
	ds_write_b32 v170, v162 offset:2080
	ds_write_b32 v170, v163 offset:3120
	v_add_u32_e32 v170, 0x30c0, v2
	ds_write_b32 v170, v164
	ds_write_b32 v170, v165 offset:1040
	ds_write_b32 v170, v166 offset:2080
	ds_write_b32 v170, v167 offset:3120
	s_branch .LBB0_74

.LBB0_727:
	v_mov_b32_e32 v152, 0
	v_mov_b32_e32 v153, 0
	v_mov_b32_e32 v154, 0
	v_mov_b32_e32 v155, 0
	v_mov_b32_e32 v156, 0
	v_mov_b32_e32 v157, 0
	v_mov_b32_e32 v158, 0
	v_mov_b32_e32 v159, 0
	v_mov_b32_e32 v160, 0
	v_mov_b32_e32 v161, 0
	v_mov_b32_e32 v162, 0
	v_mov_b32_e32 v163, 0
	v_mov_b32_e32 v164, 0
	v_mov_b32_e32 v165, 0
	v_mov_b32_e32 v166, 0
	v_mov_b32_e32 v167, 0
	s_and_saveexec_b64 s[14:15], vcc
	s_cbranch_execz .Lcvb_skip
	v_lshl_add_u64 v[168:169], v[0:1], 0, v[8:9]
	global_load_dword v152, v[168:169], off
	v_lshl_add_u64 v[168:169], v[0:1], 0, v[6:7]
	global_load_dword v153, v[168:169], off
	v_lshl_add_u64 v[168:169], v[0:1], 0, v[4:5]
	global_load_dword v154, v[168:169], off
	v_lshl_add_u64 v[168:169], v[0:1], 0, v[2:3]
	global_load_dword v155, v[168:169], off
	v_lshl_add_u64 v[0:1], v[0:1], 0, s[12:13]
	v_lshl_add_u64 v[168:169], v[0:1], 0, v[8:9]
	global_load_dword v156, v[168:169], off
	v_lshl_add_u64 v[168:169], v[0:1], 0, v[6:7]
	global_load_dword v157, v[168:169], off
	v_lshl_add_u64 v[168:169], v[0:1], 0, v[4:5]
	global_load_dword v158, v[168:169], off
	v_lshl_add_u64 v[168:169], v[0:1], 0, v[2:3]
	global_load_dword v159, v[168:169], off
	v_lshl_add_u64 v[0:1], v[0:1], 0, s[12:13]
	v_lshl_add_u64 v[168:169], v[0:1], 0, v[8:9]
	global_load_dword v160, v[168:169], off
	v_lshl_add_u64 v[168:169], v[0:1], 0, v[6:7]
	global_load_dword v161, v[168:169], off
	v_lshl_add_u64 v[168:169], v[0:1], 0, v[4:5]
	global_load_dword v162, v[168:169], off
	v_lshl_add_u64 v[168:169], v[0:1], 0, v[2:3]
	global_load_dword v163, v[168:169], off
	v_lshl_add_u64 v[0:1], v[0:1], 0, s[12:13]
	v_lshl_add_u64 v[168:169], v[0:1], 0, v[8:9]
	global_load_dword v164, v[168:169], off
	v_lshl_add_u64 v[168:169], v[0:1], 0, v[6:7]
	global_load_dword v165, v[168:169], off
	v_lshl_add_u64 v[168:169], v[0:1], 0, v[4:5]
	global_load_dword v166, v[168:169], off
	v_lshl_add_u64 v[168:169], v[0:1], 0, v[2:3]
	global_load_dword v167, v[168:169], off
	v_lshl_add_u64 v[0:1], v[0:1], 0, s[12:13]
.Lcvb_skip:
	s_or_b64 exec, exec, s[14:15]
	s_waitcnt vmcnt(0)
	v_add_u32_e32 v170, 0x0, v11
	ds_write_b32 v170, v152
	ds_write_b32 v170, v153 offset:1040
	ds_write_b32 v170, v154 offset:2080
	ds_write_b32 v170, v155 offset:3120
	v_add_u32_e32 v170, 0x1040, v11
	ds_write_b32 v170, v156
	ds_write_b32 v170, v157 offset:1040
	ds_write_b32 v170, v158 offset:2080
	ds_write_b32 v170, v159 offset:3120
	v_add_u32_e32 v170, 0x2080, v11
	ds_write_b32 v170, v160
	ds_write_b32 v170, v161 offset:1040
	ds_write_b32 v170, v162 offset:2080
	ds_write_b32 v170, v163 offset:3120
	v_add_u32_e32 v170, 0x30c0, v11
	ds_write_b32 v170, v164
	ds_write_b32 v170, v165 offset:1040
	ds_write_b32 v170, v166 offset:2080
	ds_write_b32 v170, v167 offset:3120
	s_branch .LBB0_677
